# retention phase: static s_setprio 1 for waves 4-7
# baseline (speedup 1.0000x reference)
.LBB0_43:
	s_cmp_gt_u32 s98, 3
	s_cbranch_scc0 .Lret_noprio
	s_setprio 1

.LBB0_94:
	s_setprio 0
	s_branch .LBB0_234
